# v105 + sparse tiles no longer zero the 64 O accumulators (the first sub-tile's PV MFMAs take C = 0)
# baseline (speedup 1.0000x reference)
.LBB0_839:
	s_waitcnt lgkmcnt(14)
	v_sub_u32_e32 v0, s66, v3
	v_lshlrev_b32_e32 v0, 8, v0
	v_add_u32_e32 v0, s10, v0
	v_cmp_ge_i32_e32 vcc, v0, v2
	s_cbranch_vccnz .LBB0_823
	v_mov_b32_e32 v151, 0
	s_mov_b32 s8, 0
	v_add_u32_e32 v241, 0x10000, v192
	ds_read_b128 v[224:227], v200
	ds_read_b128 v[228:231], v199
	ds_read_b128 v[232:235], v198
	ds_read_b128 v[236:239], v197
	s_setprio 1
	s_waitcnt lgkmcnt(3)
	v_mfma_f32_32x32x16_bf16 v[64:79], v[224:227], v[112:115], 0
	ds_read_b128 v[224:227], v196
	s_waitcnt lgkmcnt(3)
	v_mfma_f32_32x32x16_bf16 v[64:79], v[228:231], v[116:119], v[64:79]
	ds_read_b128 v[228:231], v195
	s_waitcnt lgkmcnt(3)
	v_mfma_f32_32x32x16_bf16 v[64:79], v[232:235], v[120:123], v[64:79]
	ds_read_b128 v[232:235], v194
	s_waitcnt lgkmcnt(3)
	v_mfma_f32_32x32x16_bf16 v[64:79], v[236:239], v[124:127], v[64:79]
	ds_read_b128 v[236:239], v193
	ds_read_b64_tr_b16 v[208:209], v241
	ds_read_b64_tr_b16 v[210:211], v241 offset:2048
	s_waitcnt lgkmcnt(5)
	v_mfma_f32_32x32x16_bf16 v[64:79], v[224:227], v[128:131], v[64:79]
	ds_read_b64_tr_b16 v[212:213], v241 offset:256
	ds_read_b64_tr_b16 v[214:215], v241 offset:2304
	s_waitcnt lgkmcnt(6)
	v_mfma_f32_32x32x16_bf16 v[64:79], v[228:231], v[132:135], v[64:79]
	ds_read_b64_tr_b16 v[216:217], v241 offset:512
	ds_read_b64_tr_b16 v[218:219], v241 offset:2560
	s_waitcnt lgkmcnt(7)
	v_mfma_f32_32x32x16_bf16 v[64:79], v[232:235], v[136:139], v[64:79]
	ds_read_b64_tr_b16 v[220:221], v241 offset:768
	ds_read_b64_tr_b16 v[222:223], v241 offset:2816
	s_waitcnt lgkmcnt(8)
	v_mfma_f32_32x32x16_bf16 v[64:79], v[236:239], v[140:143], v[64:79]
	s_setprio 0
	s_nop 7
	s_nop 3
	v_exp_f32_e32 v224, v64
	v_exp_f32_e32 v225, v65
	v_exp_f32_e32 v226, v66
	v_exp_f32_e32 v227, v67
	v_exp_f32_e32 v228, v68
	v_exp_f32_e32 v229, v69
	v_exp_f32_e32 v230, v70
	v_exp_f32_e32 v231, v71
	v_exp_f32_e32 v232, v72
	v_exp_f32_e32 v233, v73
	v_exp_f32_e32 v234, v74
	v_exp_f32_e32 v235, v75
	v_exp_f32_e32 v236, v76
	v_exp_f32_e32 v237, v77
	v_exp_f32_e32 v238, v78
	v_exp_f32_e32 v239, v79
	v_cvt_pk_bf16_f32 v64, v224, v225
	v_cvt_pk_bf16_f32 v65, v226, v227
	v_cvt_pk_bf16_f32 v66, v228, v229
	v_cvt_pk_bf16_f32 v67, v230, v231
	v_cvt_pk_bf16_f32 v68, v232, v233
	v_cvt_pk_bf16_f32 v69, v234, v235
	v_cvt_pk_bf16_f32 v70, v236, v237
	v_cvt_pk_bf16_f32 v71, v238, v239
	s_setprio 1
	s_waitcnt lgkmcnt(6)
	v_mfma_f32_32x32x16_bf16 v[48:63], v[208:211], v[64:67], 0
	ds_read_b64_tr_b16 v[208:209], v241 offset:4096
	ds_read_b64_tr_b16 v[210:211], v241 offset:6144
	v_add_f32_e32 v240, 0, v224
	v_add_f32_e32 v240, v225, v240
	v_add_f32_e32 v240, v226, v240
	v_add_f32_e32 v240, v227, v240
	v_add_f32_e32 v240, v228, v240
	s_waitcnt lgkmcnt(6)
	v_mfma_f32_32x32x16_bf16 v[32:47], v[212:215], v[64:67], 0
	ds_read_b64_tr_b16 v[212:213], v241 offset:4352
	ds_read_b64_tr_b16 v[214:215], v241 offset:6400
	v_add_f32_e32 v240, v229, v240
	v_add_f32_e32 v240, v230, v240
	v_add_f32_e32 v240, v231, v240
	v_add_f32_e32 v240, v232, v240
	s_waitcnt lgkmcnt(6)
	v_mfma_f32_32x32x16_bf16 v[16:31], v[216:219], v[64:67], 0
	ds_read_b64_tr_b16 v[216:217], v241 offset:4608
	ds_read_b64_tr_b16 v[218:219], v241 offset:6656
	v_add_f32_e32 v240, v233, v240
	v_add_f32_e32 v240, v234, v240
	v_add_f32_e32 v240, v235, v240
	v_add_f32_e32 v240, v236, v240
	s_waitcnt lgkmcnt(6)
	v_mfma_f32_32x32x16_bf16 v[0:15], v[220:223], v[64:67], 0
	ds_read_b64_tr_b16 v[220:221], v241 offset:4864
	ds_read_b64_tr_b16 v[222:223], v241 offset:6912
	v_add_f32_e32 v240, v237, v240
	v_add_f32_e32 v240, v238, v240
	v_add_f32_e32 v240, v239, v240
	v_add_f32_e32 v151, v151, v240
	s_waitcnt lgkmcnt(6)
	v_mfma_f32_32x32x16_bf16 v[48:63], v[208:211], v[68:71], v[48:63]
	ds_read_b128 v[224:227], v200 offset:8192
	s_waitcnt lgkmcnt(5)
	v_mfma_f32_32x32x16_bf16 v[32:47], v[212:215], v[68:71], v[32:47]
	ds_read_b128 v[228:231], v199 offset:8192
	s_waitcnt lgkmcnt(4)
	v_mfma_f32_32x32x16_bf16 v[16:31], v[216:219], v[68:71], v[16:31]
	ds_read_b128 v[232:235], v198 offset:8192
	s_waitcnt lgkmcnt(3)
	v_mfma_f32_32x32x16_bf16 v[0:15], v[220:223], v[68:71], v[0:15]
	ds_read_b128 v[236:239], v197 offset:8192
	s_setprio 1
	s_waitcnt lgkmcnt(3)
	v_mfma_f32_32x32x16_bf16 v[64:79], v[224:227], v[112:115], 0
	ds_read_b128 v[224:227], v196 offset:8192
	s_waitcnt lgkmcnt(3)
	v_mfma_f32_32x32x16_bf16 v[64:79], v[228:231], v[116:119], v[64:79]
	ds_read_b128 v[228:231], v195 offset:8192
	s_waitcnt lgkmcnt(3)
	v_mfma_f32_32x32x16_bf16 v[64:79], v[232:235], v[120:123], v[64:79]
	ds_read_b128 v[232:235], v194 offset:8192
	s_waitcnt lgkmcnt(3)
	v_mfma_f32_32x32x16_bf16 v[64:79], v[236:239], v[124:127], v[64:79]
	ds_read_b128 v[236:239], v193 offset:8192
	ds_read_b64_tr_b16 v[208:209], v241 offset:8192
	ds_read_b64_tr_b16 v[210:211], v241 offset:10240
	s_waitcnt lgkmcnt(5)
	v_mfma_f32_32x32x16_bf16 v[64:79], v[224:227], v[128:131], v[64:79]
	ds_read_b64_tr_b16 v[212:213], v241 offset:8448
	ds_read_b64_tr_b16 v[214:215], v241 offset:10496
	s_waitcnt lgkmcnt(6)
	v_mfma_f32_32x32x16_bf16 v[64:79], v[228:231], v[132:135], v[64:79]
	ds_read_b64_tr_b16 v[216:217], v241 offset:8704
	ds_read_b64_tr_b16 v[218:219], v241 offset:10752
	s_waitcnt lgkmcnt(7)
	v_mfma_f32_32x32x16_bf16 v[64:79], v[232:235], v[136:139], v[64:79]
	ds_read_b64_tr_b16 v[220:221], v241 offset:8960
	ds_read_b64_tr_b16 v[222:223], v241 offset:11008
	s_waitcnt lgkmcnt(8)
	v_mfma_f32_32x32x16_bf16 v[64:79], v[236:239], v[140:143], v[64:79]
	s_setprio 0
	s_nop 7
	s_nop 3
	v_exp_f32_e32 v224, v64
	v_exp_f32_e32 v225, v65
	v_exp_f32_e32 v226, v66
	v_exp_f32_e32 v227, v67
	v_exp_f32_e32 v228, v68
	v_exp_f32_e32 v229, v69
	v_exp_f32_e32 v230, v70
	v_exp_f32_e32 v231, v71
	v_exp_f32_e32 v232, v72
	v_exp_f32_e32 v233, v73
	v_exp_f32_e32 v234, v74
	v_exp_f32_e32 v235, v75
	v_exp_f32_e32 v236, v76
	v_exp_f32_e32 v237, v77
	v_exp_f32_e32 v238, v78
	v_exp_f32_e32 v239, v79
	v_cvt_pk_bf16_f32 v64, v224, v225
	v_cvt_pk_bf16_f32 v65, v226, v227
	v_cvt_pk_bf16_f32 v66, v228, v229
	v_cvt_pk_bf16_f32 v67, v230, v231
	v_cvt_pk_bf16_f32 v68, v232, v233
	v_cvt_pk_bf16_f32 v69, v234, v235
	v_cvt_pk_bf16_f32 v70, v236, v237
	v_cvt_pk_bf16_f32 v71, v238, v239
	s_setprio 1
	s_waitcnt lgkmcnt(6)
	v_mfma_f32_32x32x16_bf16 v[48:63], v[208:211], v[64:67], v[48:63]
	ds_read_b64_tr_b16 v[208:209], v241 offset:12288
	ds_read_b64_tr_b16 v[210:211], v241 offset:14336
	v_add_f32_e32 v240, 0, v224
	v_add_f32_e32 v240, v225, v240
	v_add_f32_e32 v240, v226, v240
	v_add_f32_e32 v240, v227, v240
	v_add_f32_e32 v240, v228, v240
	s_waitcnt lgkmcnt(6)
	v_mfma_f32_32x32x16_bf16 v[32:47], v[212:215], v[64:67], v[32:47]
	ds_read_b64_tr_b16 v[212:213], v241 offset:12544
	ds_read_b64_tr_b16 v[214:215], v241 offset:14592
	v_add_f32_e32 v240, v229, v240
	v_add_f32_e32 v240, v230, v240
	v_add_f32_e32 v240, v231, v240
	v_add_f32_e32 v240, v232, v240
	s_waitcnt lgkmcnt(6)
	v_mfma_f32_32x32x16_bf16 v[16:31], v[216:219], v[64:67], v[16:31]
	ds_read_b64_tr_b16 v[216:217], v241 offset:12800
	ds_read_b64_tr_b16 v[218:219], v241 offset:14848
	v_add_f32_e32 v240, v233, v240
	v_add_f32_e32 v240, v234, v240
	v_add_f32_e32 v240, v235, v240
	v_add_f32_e32 v240, v236, v240
	s_waitcnt lgkmcnt(6)
	v_mfma_f32_32x32x16_bf16 v[0:15], v[220:223], v[64:67], v[0:15]
	ds_read_b64_tr_b16 v[220:221], v241 offset:13056
	ds_read_b64_tr_b16 v[222:223], v241 offset:15104
	v_add_f32_e32 v240, v237, v240
	v_add_f32_e32 v240, v238, v240
	v_add_f32_e32 v240, v239, v240
	v_add_f32_e32 v151, v151, v240
	s_waitcnt lgkmcnt(6)
	v_mfma_f32_32x32x16_bf16 v[48:63], v[208:211], v[68:71], v[48:63]
	ds_read_b128 v[224:227], v200 offset:16384
	s_waitcnt lgkmcnt(5)
	v_mfma_f32_32x32x16_bf16 v[32:47], v[212:215], v[68:71], v[32:47]
	ds_read_b128 v[228:231], v199 offset:16384
	s_waitcnt lgkmcnt(4)
	v_mfma_f32_32x32x16_bf16 v[16:31], v[216:219], v[68:71], v[16:31]
	ds_read_b128 v[232:235], v198 offset:16384
	s_waitcnt lgkmcnt(3)
	v_mfma_f32_32x32x16_bf16 v[0:15], v[220:223], v[68:71], v[0:15]
	ds_read_b128 v[236:239], v197 offset:16384
	s_setprio 1
	s_waitcnt lgkmcnt(3)
	v_mfma_f32_32x32x16_bf16 v[64:79], v[224:227], v[112:115], 0
	ds_read_b128 v[224:227], v196 offset:16384
	s_waitcnt lgkmcnt(3)
	v_mfma_f32_32x32x16_bf16 v[64:79], v[228:231], v[116:119], v[64:79]
	ds_read_b128 v[228:231], v195 offset:16384
	s_waitcnt lgkmcnt(3)
	v_mfma_f32_32x32x16_bf16 v[64:79], v[232:235], v[120:123], v[64:79]
	ds_read_b128 v[232:235], v194 offset:16384
	s_waitcnt lgkmcnt(3)
	v_mfma_f32_32x32x16_bf16 v[64:79], v[236:239], v[124:127], v[64:79]
	ds_read_b128 v[236:239], v193 offset:16384
	ds_read_b64_tr_b16 v[208:209], v241 offset:16384
	ds_read_b64_tr_b16 v[210:211], v241 offset:18432
	s_waitcnt lgkmcnt(5)
	v_mfma_f32_32x32x16_bf16 v[64:79], v[224:227], v[128:131], v[64:79]
	ds_read_b64_tr_b16 v[212:213], v241 offset:16640
	ds_read_b64_tr_b16 v[214:215], v241 offset:18688
	s_waitcnt lgkmcnt(6)
	v_mfma_f32_32x32x16_bf16 v[64:79], v[228:231], v[132:135], v[64:79]
	ds_read_b64_tr_b16 v[216:217], v241 offset:16896
	ds_read_b64_tr_b16 v[218:219], v241 offset:18944
	s_waitcnt lgkmcnt(7)
	v_mfma_f32_32x32x16_bf16 v[64:79], v[232:235], v[136:139], v[64:79]
	ds_read_b64_tr_b16 v[220:221], v241 offset:17152
	ds_read_b64_tr_b16 v[222:223], v241 offset:19200
	s_waitcnt lgkmcnt(8)
	v_mfma_f32_32x32x16_bf16 v[64:79], v[236:239], v[140:143], v[64:79]
	s_setprio 0
	s_nop 7
	s_nop 3
	v_exp_f32_e32 v224, v64
	v_exp_f32_e32 v225, v65
	v_exp_f32_e32 v226, v66
	v_exp_f32_e32 v227, v67
	v_exp_f32_e32 v228, v68
	v_exp_f32_e32 v229, v69
	v_exp_f32_e32 v230, v70
	v_exp_f32_e32 v231, v71
	v_exp_f32_e32 v232, v72
	v_exp_f32_e32 v233, v73
	v_exp_f32_e32 v234, v74
	v_exp_f32_e32 v235, v75
	v_exp_f32_e32 v236, v76
	v_exp_f32_e32 v237, v77
	v_exp_f32_e32 v238, v78
	v_exp_f32_e32 v239, v79
	v_cvt_pk_bf16_f32 v64, v224, v225
	v_cvt_pk_bf16_f32 v65, v226, v227
	v_cvt_pk_bf16_f32 v66, v228, v229
	v_cvt_pk_bf16_f32 v67, v230, v231
	v_cvt_pk_bf16_f32 v68, v232, v233
	v_cvt_pk_bf16_f32 v69, v234, v235
	v_cvt_pk_bf16_f32 v70, v236, v237
	v_cvt_pk_bf16_f32 v71, v238, v239
	s_setprio 1
	s_waitcnt lgkmcnt(6)
	v_mfma_f32_32x32x16_bf16 v[48:63], v[208:211], v[64:67], v[48:63]
	ds_read_b64_tr_b16 v[208:209], v241 offset:20480
	ds_read_b64_tr_b16 v[210:211], v241 offset:22528
	v_add_f32_e32 v240, 0, v224
	v_add_f32_e32 v240, v225, v240
	v_add_f32_e32 v240, v226, v240
	v_add_f32_e32 v240, v227, v240
	v_add_f32_e32 v240, v228, v240
	s_waitcnt lgkmcnt(6)
	v_mfma_f32_32x32x16_bf16 v[32:47], v[212:215], v[64:67], v[32:47]
	ds_read_b64_tr_b16 v[212:213], v241 offset:20736
	ds_read_b64_tr_b16 v[214:215], v241 offset:22784
	v_add_f32_e32 v240, v229, v240
	v_add_f32_e32 v240, v230, v240
	v_add_f32_e32 v240, v231, v240
	v_add_f32_e32 v240, v232, v240
	s_waitcnt lgkmcnt(6)
	v_mfma_f32_32x32x16_bf16 v[16:31], v[216:219], v[64:67], v[16:31]
	ds_read_b64_tr_b16 v[216:217], v241 offset:20992
	ds_read_b64_tr_b16 v[218:219], v241 offset:23040
	v_add_f32_e32 v240, v233, v240
	v_add_f32_e32 v240, v234, v240
	v_add_f32_e32 v240, v235, v240
	v_add_f32_e32 v240, v236, v240
	s_waitcnt lgkmcnt(6)
	v_mfma_f32_32x32x16_bf16 v[0:15], v[220:223], v[64:67], v[0:15]
	ds_read_b64_tr_b16 v[220:221], v241 offset:21248
	ds_read_b64_tr_b16 v[222:223], v241 offset:23296
	v_add_f32_e32 v240, v237, v240
	v_add_f32_e32 v240, v238, v240
	v_add_f32_e32 v240, v239, v240
	v_add_f32_e32 v151, v151, v240
	s_waitcnt lgkmcnt(6)
	v_mfma_f32_32x32x16_bf16 v[48:63], v[208:211], v[68:71], v[48:63]
	ds_read_b128 v[224:227], v200 offset:24576
	s_waitcnt lgkmcnt(5)
	v_mfma_f32_32x32x16_bf16 v[32:47], v[212:215], v[68:71], v[32:47]
	ds_read_b128 v[228:231], v199 offset:24576
	s_waitcnt lgkmcnt(4)
	v_mfma_f32_32x32x16_bf16 v[16:31], v[216:219], v[68:71], v[16:31]
	ds_read_b128 v[232:235], v198 offset:24576
	s_waitcnt lgkmcnt(3)
	v_mfma_f32_32x32x16_bf16 v[0:15], v[220:223], v[68:71], v[0:15]
	ds_read_b128 v[236:239], v197 offset:24576
	s_setprio 1
	s_waitcnt lgkmcnt(3)
	v_mfma_f32_32x32x16_bf16 v[64:79], v[224:227], v[112:115], 0
	ds_read_b128 v[224:227], v196 offset:24576
	s_waitcnt lgkmcnt(3)
	v_mfma_f32_32x32x16_bf16 v[64:79], v[228:231], v[116:119], v[64:79]
	ds_read_b128 v[228:231], v195 offset:24576
	s_waitcnt lgkmcnt(3)
	v_mfma_f32_32x32x16_bf16 v[64:79], v[232:235], v[120:123], v[64:79]
	ds_read_b128 v[232:235], v194 offset:24576
	s_waitcnt lgkmcnt(3)
	v_mfma_f32_32x32x16_bf16 v[64:79], v[236:239], v[124:127], v[64:79]
	ds_read_b128 v[236:239], v193 offset:24576
	ds_read_b64_tr_b16 v[208:209], v241 offset:24576
	ds_read_b64_tr_b16 v[210:211], v241 offset:26624
	s_waitcnt lgkmcnt(5)
	v_mfma_f32_32x32x16_bf16 v[64:79], v[224:227], v[128:131], v[64:79]
	ds_read_b64_tr_b16 v[212:213], v241 offset:24832
	ds_read_b64_tr_b16 v[214:215], v241 offset:26880
	s_waitcnt lgkmcnt(6)
	v_mfma_f32_32x32x16_bf16 v[64:79], v[228:231], v[132:135], v[64:79]
	ds_read_b64_tr_b16 v[216:217], v241 offset:25088
	ds_read_b64_tr_b16 v[218:219], v241 offset:27136
	s_waitcnt lgkmcnt(7)
	v_mfma_f32_32x32x16_bf16 v[64:79], v[232:235], v[136:139], v[64:79]
	ds_read_b64_tr_b16 v[220:221], v241 offset:25344
	ds_read_b64_tr_b16 v[222:223], v241 offset:27392
	s_waitcnt lgkmcnt(8)
	v_mfma_f32_32x32x16_bf16 v[64:79], v[236:239], v[140:143], v[64:79]
	s_setprio 0
	s_nop 7
	s_nop 3
	v_exp_f32_e32 v224, v64
	v_exp_f32_e32 v225, v65
	v_exp_f32_e32 v226, v66
	v_exp_f32_e32 v227, v67
	v_exp_f32_e32 v228, v68
	v_exp_f32_e32 v229, v69
	v_exp_f32_e32 v230, v70
	v_exp_f32_e32 v231, v71
	v_exp_f32_e32 v232, v72
	v_exp_f32_e32 v233, v73
	v_exp_f32_e32 v234, v74
	v_exp_f32_e32 v235, v75
	v_exp_f32_e32 v236, v76
	v_exp_f32_e32 v237, v77
	v_exp_f32_e32 v238, v78
	v_exp_f32_e32 v239, v79
	v_cvt_pk_bf16_f32 v64, v224, v225
	v_cvt_pk_bf16_f32 v65, v226, v227
	v_cvt_pk_bf16_f32 v66, v228, v229
	v_cvt_pk_bf16_f32 v67, v230, v231
	v_cvt_pk_bf16_f32 v68, v232, v233
	v_cvt_pk_bf16_f32 v69, v234, v235
	v_cvt_pk_bf16_f32 v70, v236, v237
	v_cvt_pk_bf16_f32 v71, v238, v239
	s_setprio 1
	s_waitcnt lgkmcnt(6)
	v_mfma_f32_32x32x16_bf16 v[48:63], v[208:211], v[64:67], v[48:63]
	ds_read_b64_tr_b16 v[208:209], v241 offset:28672
	ds_read_b64_tr_b16 v[210:211], v241 offset:30720
	v_add_f32_e32 v240, 0, v224
	v_add_f32_e32 v240, v225, v240
	v_add_f32_e32 v240, v226, v240
	v_add_f32_e32 v240, v227, v240
	v_add_f32_e32 v240, v228, v240
	s_waitcnt lgkmcnt(6)
	v_mfma_f32_32x32x16_bf16 v[32:47], v[212:215], v[64:67], v[32:47]
	ds_read_b64_tr_b16 v[212:213], v241 offset:28928
	ds_read_b64_tr_b16 v[214:215], v241 offset:30976
	v_add_f32_e32 v240, v229, v240
	v_add_f32_e32 v240, v230, v240
	v_add_f32_e32 v240, v231, v240
	v_add_f32_e32 v240, v232, v240
	s_waitcnt lgkmcnt(6)
	v_mfma_f32_32x32x16_bf16 v[16:31], v[216:219], v[64:67], v[16:31]
	ds_read_b64_tr_b16 v[216:217], v241 offset:29184
	ds_read_b64_tr_b16 v[218:219], v241 offset:31232
	v_add_f32_e32 v240, v233, v240
	v_add_f32_e32 v240, v234, v240
	v_add_f32_e32 v240, v235, v240
	v_add_f32_e32 v240, v236, v240
	s_waitcnt lgkmcnt(6)
	v_mfma_f32_32x32x16_bf16 v[0:15], v[220:223], v[64:67], v[0:15]
	ds_read_b64_tr_b16 v[220:221], v241 offset:29440
	ds_read_b64_tr_b16 v[222:223], v241 offset:31488
	v_add_f32_e32 v240, v237, v240
	v_add_f32_e32 v240, v238, v240
	v_add_f32_e32 v240, v239, v240
	v_add_f32_e32 v151, v151, v240
	s_waitcnt lgkmcnt(6)
	v_mfma_f32_32x32x16_bf16 v[48:63], v[208:211], v[68:71], v[48:63]
	ds_read_b128 v[224:227], v200 offset:32768
	s_waitcnt lgkmcnt(5)
	v_mfma_f32_32x32x16_bf16 v[32:47], v[212:215], v[68:71], v[32:47]
	ds_read_b128 v[228:231], v199 offset:32768
	s_waitcnt lgkmcnt(4)
	v_mfma_f32_32x32x16_bf16 v[16:31], v[216:219], v[68:71], v[16:31]
	ds_read_b128 v[232:235], v198 offset:32768
	s_waitcnt lgkmcnt(3)
	v_mfma_f32_32x32x16_bf16 v[0:15], v[220:223], v[68:71], v[0:15]
	ds_read_b128 v[236:239], v197 offset:32768
	s_setprio 1
	s_waitcnt lgkmcnt(3)
	v_mfma_f32_32x32x16_bf16 v[64:79], v[224:227], v[112:115], 0
	ds_read_b128 v[224:227], v196 offset:32768
	s_waitcnt lgkmcnt(3)
	v_mfma_f32_32x32x16_bf16 v[64:79], v[228:231], v[116:119], v[64:79]
	ds_read_b128 v[228:231], v195 offset:32768
	s_waitcnt lgkmcnt(3)
	v_mfma_f32_32x32x16_bf16 v[64:79], v[232:235], v[120:123], v[64:79]
	ds_read_b128 v[232:235], v194 offset:32768
	s_waitcnt lgkmcnt(3)
	v_mfma_f32_32x32x16_bf16 v[64:79], v[236:239], v[124:127], v[64:79]
	ds_read_b128 v[236:239], v193 offset:32768
	ds_read_b64_tr_b16 v[208:209], v241 offset:32768
	ds_read_b64_tr_b16 v[210:211], v241 offset:34816
	s_waitcnt lgkmcnt(5)
	v_mfma_f32_32x32x16_bf16 v[64:79], v[224:227], v[128:131], v[64:79]
	ds_read_b64_tr_b16 v[212:213], v241 offset:33024
	ds_read_b64_tr_b16 v[214:215], v241 offset:35072
	s_waitcnt lgkmcnt(6)
	v_mfma_f32_32x32x16_bf16 v[64:79], v[228:231], v[132:135], v[64:79]
	ds_read_b64_tr_b16 v[216:217], v241 offset:33280
	ds_read_b64_tr_b16 v[218:219], v241 offset:35328
	s_waitcnt lgkmcnt(7)
	v_mfma_f32_32x32x16_bf16 v[64:79], v[232:235], v[136:139], v[64:79]
	ds_read_b64_tr_b16 v[220:221], v241 offset:33536
	ds_read_b64_tr_b16 v[222:223], v241 offset:35584
	s_waitcnt lgkmcnt(8)
	v_mfma_f32_32x32x16_bf16 v[64:79], v[236:239], v[140:143], v[64:79]
	s_setprio 0
	s_nop 7
	s_nop 3
	v_exp_f32_e32 v224, v64
	v_exp_f32_e32 v225, v65
	v_exp_f32_e32 v226, v66
	v_exp_f32_e32 v227, v67
	v_exp_f32_e32 v228, v68
	v_exp_f32_e32 v229, v69
	v_exp_f32_e32 v230, v70
	v_exp_f32_e32 v231, v71
	v_exp_f32_e32 v232, v72
	v_exp_f32_e32 v233, v73
	v_exp_f32_e32 v234, v74
	v_exp_f32_e32 v235, v75
	v_exp_f32_e32 v236, v76
	v_exp_f32_e32 v237, v77
	v_exp_f32_e32 v238, v78
	v_exp_f32_e32 v239, v79
	v_cvt_pk_bf16_f32 v64, v224, v225
	v_cvt_pk_bf16_f32 v65, v226, v227
	v_cvt_pk_bf16_f32 v66, v228, v229
	v_cvt_pk_bf16_f32 v67, v230, v231
	v_cvt_pk_bf16_f32 v68, v232, v233
	v_cvt_pk_bf16_f32 v69, v234, v235
	v_cvt_pk_bf16_f32 v70, v236, v237
	v_cvt_pk_bf16_f32 v71, v238, v239
	s_setprio 1
	s_waitcnt lgkmcnt(6)
	v_mfma_f32_32x32x16_bf16 v[48:63], v[208:211], v[64:67], v[48:63]
	ds_read_b64_tr_b16 v[208:209], v241 offset:36864
	ds_read_b64_tr_b16 v[210:211], v241 offset:38912
	v_add_f32_e32 v240, 0, v224
	v_add_f32_e32 v240, v225, v240
	v_add_f32_e32 v240, v226, v240
	v_add_f32_e32 v240, v227, v240
	v_add_f32_e32 v240, v228, v240
	s_waitcnt lgkmcnt(6)
	v_mfma_f32_32x32x16_bf16 v[32:47], v[212:215], v[64:67], v[32:47]
	ds_read_b64_tr_b16 v[212:213], v241 offset:37120
	ds_read_b64_tr_b16 v[214:215], v241 offset:39168
	v_add_f32_e32 v240, v229, v240
	v_add_f32_e32 v240, v230, v240
	v_add_f32_e32 v240, v231, v240
	v_add_f32_e32 v240, v232, v240
	s_waitcnt lgkmcnt(6)
	v_mfma_f32_32x32x16_bf16 v[16:31], v[216:219], v[64:67], v[16:31]
	ds_read_b64_tr_b16 v[216:217], v241 offset:37376
	ds_read_b64_tr_b16 v[218:219], v241 offset:39424
	v_add_f32_e32 v240, v233, v240
	v_add_f32_e32 v240, v234, v240
	v_add_f32_e32 v240, v235, v240
	v_add_f32_e32 v240, v236, v240
	s_waitcnt lgkmcnt(6)
	v_mfma_f32_32x32x16_bf16 v[0:15], v[220:223], v[64:67], v[0:15]
	ds_read_b64_tr_b16 v[220:221], v241 offset:37632
	ds_read_b64_tr_b16 v[222:223], v241 offset:39680
	v_add_f32_e32 v240, v237, v240
	v_add_f32_e32 v240, v238, v240
	v_add_f32_e32 v240, v239, v240
	v_add_f32_e32 v151, v151, v240
	s_waitcnt lgkmcnt(6)
	v_mfma_f32_32x32x16_bf16 v[48:63], v[208:211], v[68:71], v[48:63]
	ds_read_b128 v[224:227], v200 offset:40960
	s_waitcnt lgkmcnt(5)
	v_mfma_f32_32x32x16_bf16 v[32:47], v[212:215], v[68:71], v[32:47]
	ds_read_b128 v[228:231], v199 offset:40960
	s_waitcnt lgkmcnt(4)
	v_mfma_f32_32x32x16_bf16 v[16:31], v[216:219], v[68:71], v[16:31]
	ds_read_b128 v[232:235], v198 offset:40960
	s_waitcnt lgkmcnt(3)
	v_mfma_f32_32x32x16_bf16 v[0:15], v[220:223], v[68:71], v[0:15]
	ds_read_b128 v[236:239], v197 offset:40960
	s_setprio 1
	s_waitcnt lgkmcnt(3)
	v_mfma_f32_32x32x16_bf16 v[64:79], v[224:227], v[112:115], 0
	ds_read_b128 v[224:227], v196 offset:40960
	s_waitcnt lgkmcnt(3)
	v_mfma_f32_32x32x16_bf16 v[64:79], v[228:231], v[116:119], v[64:79]
	ds_read_b128 v[228:231], v195 offset:40960
	s_waitcnt lgkmcnt(3)
	v_mfma_f32_32x32x16_bf16 v[64:79], v[232:235], v[120:123], v[64:79]
	ds_read_b128 v[232:235], v194 offset:40960
	s_waitcnt lgkmcnt(3)
	v_mfma_f32_32x32x16_bf16 v[64:79], v[236:239], v[124:127], v[64:79]
	ds_read_b128 v[236:239], v193 offset:40960
	ds_read_b64_tr_b16 v[208:209], v241 offset:40960
	ds_read_b64_tr_b16 v[210:211], v241 offset:43008
	s_waitcnt lgkmcnt(5)
	v_mfma_f32_32x32x16_bf16 v[64:79], v[224:227], v[128:131], v[64:79]
	ds_read_b64_tr_b16 v[212:213], v241 offset:41216
	ds_read_b64_tr_b16 v[214:215], v241 offset:43264
	s_waitcnt lgkmcnt(6)
	v_mfma_f32_32x32x16_bf16 v[64:79], v[228:231], v[132:135], v[64:79]
	ds_read_b64_tr_b16 v[216:217], v241 offset:41472
	ds_read_b64_tr_b16 v[218:219], v241 offset:43520
	s_waitcnt lgkmcnt(7)
	v_mfma_f32_32x32x16_bf16 v[64:79], v[232:235], v[136:139], v[64:79]
	ds_read_b64_tr_b16 v[220:221], v241 offset:41728
	ds_read_b64_tr_b16 v[222:223], v241 offset:43776
	s_waitcnt lgkmcnt(8)
	v_mfma_f32_32x32x16_bf16 v[64:79], v[236:239], v[140:143], v[64:79]
	s_setprio 0
	s_nop 7
	s_nop 3
	v_exp_f32_e32 v224, v64
	v_exp_f32_e32 v225, v65
	v_exp_f32_e32 v226, v66
	v_exp_f32_e32 v227, v67
	v_exp_f32_e32 v228, v68
	v_exp_f32_e32 v229, v69
	v_exp_f32_e32 v230, v70
	v_exp_f32_e32 v231, v71
	v_exp_f32_e32 v232, v72
	v_exp_f32_e32 v233, v73
	v_exp_f32_e32 v234, v74
	v_exp_f32_e32 v235, v75
	v_exp_f32_e32 v236, v76
	v_exp_f32_e32 v237, v77
	v_exp_f32_e32 v238, v78
	v_exp_f32_e32 v239, v79
	v_cvt_pk_bf16_f32 v64, v224, v225
	v_cvt_pk_bf16_f32 v65, v226, v227
	v_cvt_pk_bf16_f32 v66, v228, v229
	v_cvt_pk_bf16_f32 v67, v230, v231
	v_cvt_pk_bf16_f32 v68, v232, v233
	v_cvt_pk_bf16_f32 v69, v234, v235
	v_cvt_pk_bf16_f32 v70, v236, v237
	v_cvt_pk_bf16_f32 v71, v238, v239
	s_setprio 1
	s_waitcnt lgkmcnt(6)
	v_mfma_f32_32x32x16_bf16 v[48:63], v[208:211], v[64:67], v[48:63]
	ds_read_b64_tr_b16 v[208:209], v241 offset:45056
	ds_read_b64_tr_b16 v[210:211], v241 offset:47104
	v_add_f32_e32 v240, 0, v224
	v_add_f32_e32 v240, v225, v240
	v_add_f32_e32 v240, v226, v240
	v_add_f32_e32 v240, v227, v240
	v_add_f32_e32 v240, v228, v240
	s_waitcnt lgkmcnt(6)
	v_mfma_f32_32x32x16_bf16 v[32:47], v[212:215], v[64:67], v[32:47]
	ds_read_b64_tr_b16 v[212:213], v241 offset:45312
	ds_read_b64_tr_b16 v[214:215], v241 offset:47360
	v_add_f32_e32 v240, v229, v240
	v_add_f32_e32 v240, v230, v240
	v_add_f32_e32 v240, v231, v240
	v_add_f32_e32 v240, v232, v240
	s_waitcnt lgkmcnt(6)
	v_mfma_f32_32x32x16_bf16 v[16:31], v[216:219], v[64:67], v[16:31]
	ds_read_b64_tr_b16 v[216:217], v241 offset:45568
	ds_read_b64_tr_b16 v[218:219], v241 offset:47616
	v_add_f32_e32 v240, v233, v240
	v_add_f32_e32 v240, v234, v240
	v_add_f32_e32 v240, v235, v240
	v_add_f32_e32 v240, v236, v240
	s_waitcnt lgkmcnt(6)
	v_mfma_f32_32x32x16_bf16 v[0:15], v[220:223], v[64:67], v[0:15]
	ds_read_b64_tr_b16 v[220:221], v241 offset:45824
	ds_read_b64_tr_b16 v[222:223], v241 offset:47872
	v_add_f32_e32 v240, v237, v240
	v_add_f32_e32 v240, v238, v240
	v_add_f32_e32 v240, v239, v240
	v_add_f32_e32 v151, v151, v240
	s_waitcnt lgkmcnt(6)
	v_mfma_f32_32x32x16_bf16 v[48:63], v[208:211], v[68:71], v[48:63]
	ds_read_b128 v[224:227], v200 offset:49152
	s_waitcnt lgkmcnt(5)
	v_mfma_f32_32x32x16_bf16 v[32:47], v[212:215], v[68:71], v[32:47]
	ds_read_b128 v[228:231], v199 offset:49152
	s_waitcnt lgkmcnt(4)
	v_mfma_f32_32x32x16_bf16 v[16:31], v[216:219], v[68:71], v[16:31]
	ds_read_b128 v[232:235], v198 offset:49152
	s_waitcnt lgkmcnt(3)
	v_mfma_f32_32x32x16_bf16 v[0:15], v[220:223], v[68:71], v[0:15]
	ds_read_b128 v[236:239], v197 offset:49152
	s_setprio 1
	s_waitcnt lgkmcnt(3)
	v_mfma_f32_32x32x16_bf16 v[64:79], v[224:227], v[112:115], 0
	ds_read_b128 v[224:227], v196 offset:49152
	s_waitcnt lgkmcnt(3)
	v_mfma_f32_32x32x16_bf16 v[64:79], v[228:231], v[116:119], v[64:79]
	ds_read_b128 v[228:231], v195 offset:49152
	s_waitcnt lgkmcnt(3)
	v_mfma_f32_32x32x16_bf16 v[64:79], v[232:235], v[120:123], v[64:79]
	ds_read_b128 v[232:235], v194 offset:49152
	s_waitcnt lgkmcnt(3)
	v_mfma_f32_32x32x16_bf16 v[64:79], v[236:239], v[124:127], v[64:79]
	ds_read_b128 v[236:239], v193 offset:49152
	ds_read_b64_tr_b16 v[208:209], v241 offset:49152
	ds_read_b64_tr_b16 v[210:211], v241 offset:51200
	s_waitcnt lgkmcnt(5)
	v_mfma_f32_32x32x16_bf16 v[64:79], v[224:227], v[128:131], v[64:79]
	ds_read_b64_tr_b16 v[212:213], v241 offset:49408
	ds_read_b64_tr_b16 v[214:215], v241 offset:51456
	s_waitcnt lgkmcnt(6)
	v_mfma_f32_32x32x16_bf16 v[64:79], v[228:231], v[132:135], v[64:79]
	ds_read_b64_tr_b16 v[216:217], v241 offset:49664
	ds_read_b64_tr_b16 v[218:219], v241 offset:51712
	s_waitcnt lgkmcnt(7)
	v_mfma_f32_32x32x16_bf16 v[64:79], v[232:235], v[136:139], v[64:79]
	ds_read_b64_tr_b16 v[220:221], v241 offset:49920
	ds_read_b64_tr_b16 v[222:223], v241 offset:51968
	s_waitcnt lgkmcnt(8)
	v_mfma_f32_32x32x16_bf16 v[64:79], v[236:239], v[140:143], v[64:79]
	s_setprio 0
	s_nop 7
	s_nop 3
	v_exp_f32_e32 v224, v64
	v_exp_f32_e32 v225, v65
	v_exp_f32_e32 v226, v66
	v_exp_f32_e32 v227, v67
	v_exp_f32_e32 v228, v68
	v_exp_f32_e32 v229, v69
	v_exp_f32_e32 v230, v70
	v_exp_f32_e32 v231, v71
	v_exp_f32_e32 v232, v72
	v_exp_f32_e32 v233, v73
	v_exp_f32_e32 v234, v74
	v_exp_f32_e32 v235, v75
	v_exp_f32_e32 v236, v76
	v_exp_f32_e32 v237, v77
	v_exp_f32_e32 v238, v78
	v_exp_f32_e32 v239, v79
	v_cvt_pk_bf16_f32 v64, v224, v225
	v_cvt_pk_bf16_f32 v65, v226, v227
	v_cvt_pk_bf16_f32 v66, v228, v229
	v_cvt_pk_bf16_f32 v67, v230, v231
	v_cvt_pk_bf16_f32 v68, v232, v233
	v_cvt_pk_bf16_f32 v69, v234, v235
	v_cvt_pk_bf16_f32 v70, v236, v237
	v_cvt_pk_bf16_f32 v71, v238, v239
	s_setprio 1
	s_waitcnt lgkmcnt(6)
	v_mfma_f32_32x32x16_bf16 v[48:63], v[208:211], v[64:67], v[48:63]
	ds_read_b64_tr_b16 v[208:209], v241 offset:53248
	ds_read_b64_tr_b16 v[210:211], v241 offset:55296
	v_add_f32_e32 v240, 0, v224
	v_add_f32_e32 v240, v225, v240
	v_add_f32_e32 v240, v226, v240
	v_add_f32_e32 v240, v227, v240
	v_add_f32_e32 v240, v228, v240
	s_waitcnt lgkmcnt(6)
	v_mfma_f32_32x32x16_bf16 v[32:47], v[212:215], v[64:67], v[32:47]
	ds_read_b64_tr_b16 v[212:213], v241 offset:53504
	ds_read_b64_tr_b16 v[214:215], v241 offset:55552
	v_add_f32_e32 v240, v229, v240
	v_add_f32_e32 v240, v230, v240
	v_add_f32_e32 v240, v231, v240
	v_add_f32_e32 v240, v232, v240
	s_waitcnt lgkmcnt(6)
	v_mfma_f32_32x32x16_bf16 v[16:31], v[216:219], v[64:67], v[16:31]
	ds_read_b64_tr_b16 v[216:217], v241 offset:53760
	ds_read_b64_tr_b16 v[218:219], v241 offset:55808
	v_add_f32_e32 v240, v233, v240
	v_add_f32_e32 v240, v234, v240
	v_add_f32_e32 v240, v235, v240
	v_add_f32_e32 v240, v236, v240
	s_waitcnt lgkmcnt(6)
	v_mfma_f32_32x32x16_bf16 v[0:15], v[220:223], v[64:67], v[0:15]
	ds_read_b64_tr_b16 v[220:221], v241 offset:54016
	ds_read_b64_tr_b16 v[222:223], v241 offset:56064
	v_add_f32_e32 v240, v237, v240
	v_add_f32_e32 v240, v238, v240
	v_add_f32_e32 v240, v239, v240
	v_add_f32_e32 v151, v151, v240
	s_waitcnt lgkmcnt(6)
	v_mfma_f32_32x32x16_bf16 v[48:63], v[208:211], v[68:71], v[48:63]
	ds_read_b128 v[224:227], v200 offset:57344
	s_waitcnt lgkmcnt(5)
	v_mfma_f32_32x32x16_bf16 v[32:47], v[212:215], v[68:71], v[32:47]
	ds_read_b128 v[228:231], v199 offset:57344
	s_waitcnt lgkmcnt(4)
	v_mfma_f32_32x32x16_bf16 v[16:31], v[216:219], v[68:71], v[16:31]
	ds_read_b128 v[232:235], v198 offset:57344
	s_waitcnt lgkmcnt(3)
	v_mfma_f32_32x32x16_bf16 v[0:15], v[220:223], v[68:71], v[0:15]
	ds_read_b128 v[236:239], v197 offset:57344
	s_setprio 1
	s_waitcnt lgkmcnt(3)
	v_mfma_f32_32x32x16_bf16 v[64:79], v[224:227], v[112:115], 0
	ds_read_b128 v[224:227], v196 offset:57344
	s_waitcnt lgkmcnt(3)
	v_mfma_f32_32x32x16_bf16 v[64:79], v[228:231], v[116:119], v[64:79]
	ds_read_b128 v[228:231], v195 offset:57344
	s_waitcnt lgkmcnt(3)
	v_mfma_f32_32x32x16_bf16 v[64:79], v[232:235], v[120:123], v[64:79]
	ds_read_b128 v[232:235], v194 offset:57344
	s_waitcnt lgkmcnt(3)
	v_mfma_f32_32x32x16_bf16 v[64:79], v[236:239], v[124:127], v[64:79]
	ds_read_b128 v[236:239], v193 offset:57344
	ds_read_b64_tr_b16 v[208:209], v241 offset:57344
	ds_read_b64_tr_b16 v[210:211], v241 offset:59392
	s_waitcnt lgkmcnt(5)
	v_mfma_f32_32x32x16_bf16 v[64:79], v[224:227], v[128:131], v[64:79]
	ds_read_b64_tr_b16 v[212:213], v241 offset:57600
	ds_read_b64_tr_b16 v[214:215], v241 offset:59648
	s_waitcnt lgkmcnt(6)
	v_mfma_f32_32x32x16_bf16 v[64:79], v[228:231], v[132:135], v[64:79]
	ds_read_b64_tr_b16 v[216:217], v241 offset:57856
	ds_read_b64_tr_b16 v[218:219], v241 offset:59904
	s_waitcnt lgkmcnt(7)
	v_mfma_f32_32x32x16_bf16 v[64:79], v[232:235], v[136:139], v[64:79]
	ds_read_b64_tr_b16 v[220:221], v241 offset:58112
	ds_read_b64_tr_b16 v[222:223], v241 offset:60160
	s_waitcnt lgkmcnt(8)
	v_mfma_f32_32x32x16_bf16 v[64:79], v[236:239], v[140:143], v[64:79]
	s_setprio 0
	s_nop 7
	s_nop 3
	v_exp_f32_e32 v224, v64
	v_exp_f32_e32 v225, v65
	v_exp_f32_e32 v226, v66
	v_exp_f32_e32 v227, v67
	v_exp_f32_e32 v228, v68
	v_exp_f32_e32 v229, v69
	v_exp_f32_e32 v230, v70
	v_exp_f32_e32 v231, v71
	v_exp_f32_e32 v232, v72
	v_exp_f32_e32 v233, v73
	v_exp_f32_e32 v234, v74
	v_exp_f32_e32 v235, v75
	v_exp_f32_e32 v236, v76
	v_exp_f32_e32 v237, v77
	v_exp_f32_e32 v238, v78
	v_exp_f32_e32 v239, v79
	v_cvt_pk_bf16_f32 v64, v224, v225
	v_cvt_pk_bf16_f32 v65, v226, v227
	v_cvt_pk_bf16_f32 v66, v228, v229
	v_cvt_pk_bf16_f32 v67, v230, v231
	v_cvt_pk_bf16_f32 v68, v232, v233
	v_cvt_pk_bf16_f32 v69, v234, v235
	v_cvt_pk_bf16_f32 v70, v236, v237
	v_cvt_pk_bf16_f32 v71, v238, v239
	s_setprio 1
	s_waitcnt lgkmcnt(6)
	v_mfma_f32_32x32x16_bf16 v[48:63], v[208:211], v[64:67], v[48:63]
	ds_read_b64_tr_b16 v[208:209], v241 offset:61440
	ds_read_b64_tr_b16 v[210:211], v241 offset:63488
	v_add_f32_e32 v240, 0, v224
	v_add_f32_e32 v240, v225, v240
	v_add_f32_e32 v240, v226, v240
	v_add_f32_e32 v240, v227, v240
	v_add_f32_e32 v240, v228, v240
	s_waitcnt lgkmcnt(6)
	v_mfma_f32_32x32x16_bf16 v[32:47], v[212:215], v[64:67], v[32:47]
	ds_read_b64_tr_b16 v[212:213], v241 offset:61696
	ds_read_b64_tr_b16 v[214:215], v241 offset:63744
	v_add_f32_e32 v240, v229, v240
	v_add_f32_e32 v240, v230, v240
	v_add_f32_e32 v240, v231, v240
	v_add_f32_e32 v240, v232, v240
	s_waitcnt lgkmcnt(6)
	v_mfma_f32_32x32x16_bf16 v[16:31], v[216:219], v[64:67], v[16:31]
	ds_read_b64_tr_b16 v[216:217], v241 offset:61952
	ds_read_b64_tr_b16 v[218:219], v241 offset:64000
	v_add_f32_e32 v240, v233, v240
	v_add_f32_e32 v240, v234, v240
	v_add_f32_e32 v240, v235, v240
	v_add_f32_e32 v240, v236, v240
	s_waitcnt lgkmcnt(6)
	v_mfma_f32_32x32x16_bf16 v[0:15], v[220:223], v[64:67], v[0:15]
	ds_read_b64_tr_b16 v[220:221], v241 offset:62208
	ds_read_b64_tr_b16 v[222:223], v241 offset:64256
	v_add_f32_e32 v240, v237, v240
	v_add_f32_e32 v240, v238, v240
	v_add_f32_e32 v240, v239, v240
	v_add_f32_e32 v151, v151, v240
	s_waitcnt lgkmcnt(6)
	v_mfma_f32_32x32x16_bf16 v[48:63], v[208:211], v[68:71], v[48:63]
	s_waitcnt lgkmcnt(4)
	v_mfma_f32_32x32x16_bf16 v[32:47], v[212:215], v[68:71], v[32:47]
	s_waitcnt lgkmcnt(2)
	v_mfma_f32_32x32x16_bf16 v[16:31], v[216:219], v[68:71], v[16:31]
	s_waitcnt lgkmcnt(0)
	v_mfma_f32_32x32x16_bf16 v[0:15], v[220:223], v[68:71], v[0:15]
	s_waitcnt lgkmcnt(0)
	s_setprio 0
	ds_bpermute_b32 v66, v191, v151
	v_lshrrev_b32_e32 v65, 2, v207
	v_cmp_ne_u32_e32 vcc, -1, v207
	v_and_b32_e32 v64, 3, v207
	v_lshl_add_u32 v65, s68, 13, v65
	v_mad_u64_u32 v[64:65], s[8:9], v65, 3, v[64:65]
	s_and_b64 s[30:31], vcc, s[4:5]
	s_and_saveexec_b64 s[8:9], s[30:31]
	s_cbranch_execz .LBB0_844
	v_ashrrev_i32_e32 v65, 31, v64
	s_waitcnt lgkmcnt(0)
	v_add_f32_e32 v68, v151, v66
	v_lshl_add_u64 v[66:67], v[64:65], 2, s[36:37]
	global_store_dword v[66:67], v68, off
	s_add_u32 s98, s98, 1
